# HGRN scan: dv broadcast pairs loaded as (x,x) by ds_read2 with equal offsets, state update uses plain packed fma without op_sel, no per-step copies
# baseline (speedup 1.0000x reference)
; #define HG_LD(X, tl_) do { const float* f_ = sF + (tl_) * 128 + seg * 4; const float* q_ = sQ + (tl_) * 128 + seg * 4;   \
;                 X##f0 = *(const f32x4*)(f_); X##f1 = *(const f32x4*)(f_ + 64); X##q0 = *(const f32x4*)(q_); X##q1 = *(const f32x4*)(q_ + 64); \
;                 X##va = sDV[(tl_) * 64 + cp]; X##vb = sDV[(tl_) * 64 + 32 + cp]; } while (0)
; __device__ __forceinline__ void phase_hgrn(KP P, int l_, unsigned char* shm) {
;     ...
;             {
;                 f32x4 Af0, Af1, Aq0, Aq1; float Ava, Avb;
;                 f32x4 Bf0, Bf1, Bq0, Bq1; float Bva, Bvb;
;                 HG_LD(A, 0);
.LBB0_2162:
	ds_read_b128 v[18:21], v111
	ds_read_b128 v[14:17], v111 offset:256
	ds_read_b128 v[10:13], v111 offset:16384
	ds_read_b128 v[6:9], v111 offset:16640
	ds_read2_b32 v[78:79], v116
	ds_read2_b32 v[140:141], v116 offset0:32 offset1:32
	s_mov_b32 s17, -2
	v_mov_b32_e32 v129, v110
	v_mov_b32_e32 v130, v109
	v_mov_b32_e32 v131, v108
	v_mov_b32_e32 v132, v107
	s_waitcnt lgkmcnt(0)
	s_branch .LBB0_2164

; #define HG_LD(X, tl_) do { const float* f_ = sF + (tl_) * 128 + seg * 4; const float* q_ = sQ + (tl_) * 128 + seg * 4;   \
;                 X##f0 = *(const f32x4*)(f_); X##f1 = *(const f32x4*)(f_ + 64); X##q0 = *(const f32x4*)(q_); X##q1 = *(const f32x4*)(q_ + 64); \
;                 X##va = sDV[(tl_) * 64 + cp]; X##vb = sDV[(tl_) * 64 + 32 + cp]; } while (0)
; __device__ __forceinline__ void phase_hgrn(KP P, int l_, unsigned char* shm) {
;     ...
;             {
;                 f32x4 Af0, Af1, Aq0, Aq1; float Ava, Avb;
;                 f32x4 Bf0, Bf1, Bq0, Bq1; float Bva, Bvb;
;                 HG_LD(A, 0);
; #pragma unroll 2
;                 for (int tl = 0; tl < T; tl += 2) {
;                     HG_LD(B, tl + 1);
;                     HG_STEP(A, tl);
;                     HG_LD(A, tl + 2);
;                     HG_STEP(B, tl + 1);
;                 }
.LBB0_2164:
	ds_read_b128 v[34:37], v129
	ds_read_b128 v[30:33], v129 offset:256
	ds_read_b128 v[26:29], v129 offset:16384
	ds_read_b128 v[22:25], v129 offset:16640
	ds_read2_b32 v[80:81], v130
	ds_read2_b32 v[142:143], v130 offset0:32 offset1:32
	s_waitcnt lgkmcnt(10)
	v_pk_fma_f32 v[70:71], v[20:21], v[70:71], v[78:79]
	v_pk_fma_f32 v[76:77], v[20:21], v[76:77], v[140:141]
	v_pk_fma_f32 v[64:65], v[18:19], v[64:65], v[78:79]
	v_pk_fma_f32 v[82:83], v[18:19], v[62:63], v[140:141]
	s_waitcnt lgkmcnt(9)
	v_pk_fma_f32 v[68:69], v[14:15], v[68:69], v[78:79]
	v_pk_fma_f32 v[74:75], v[14:15], v[74:75], v[140:141]
	v_pk_fma_f32 v[66:67], v[16:17], v[66:67], v[78:79]
	v_pk_fma_f32 v[72:73], v[16:17], v[72:73], v[140:141]
	s_waitcnt lgkmcnt(8)
	v_pk_mul_f32 v[14:15], v[12:13], v[70:71]
	v_pk_mul_f32 v[12:13], v[12:13], v[76:77]
	v_pk_fma_f32 v[14:15], v[10:11], v[64:65], v[14:15]
	v_pk_fma_f32 v[10:11], v[10:11], v[82:83], v[12:13]
	s_waitcnt lgkmcnt(8)
	v_pk_fma_f32 v[12:13], v[8:9], v[66:67], v[14:15]
	v_pk_fma_f32 v[8:9], v[8:9], v[72:73], v[10:11]
	v_pk_fma_f32 v[12:13], v[6:7], v[68:69], v[12:13]
	v_pk_fma_f32 v[6:7], v[6:7], v[74:75], v[8:9]
	v_add_f32_e32 v4, v12, v13
	v_add_f32_e32 v6, v6, v7
	s_nop 0
	v_add_f32_dpp v4, v4, v4 quad_perm:[1,0,3,2] row_mask:0xf bank_mask:0xf bound_ctrl:1
	v_add_f32_dpp v6, v6, v6 quad_perm:[1,0,3,2] row_mask:0xf bank_mask:0xf bound_ctrl:1
	s_nop 0
	v_add_f32_dpp v4, v4, v4 quad_perm:[2,3,0,1] row_mask:0xf bank_mask:0xf bound_ctrl:1
	v_add_f32_dpp v6, v6, v6 quad_perm:[2,3,0,1] row_mask:0xf bank_mask:0xf bound_ctrl:1
	s_and_saveexec_b64 s[22:23], s[8:9]
	s_cbranch_execz .LBB0_2166
	ds_write_b32 v132, v4
	ds_write_b32 v131, v6
.LBB0_2166:
	s_or_b64 exec, exec, s[22:23]
	s_waitcnt lgkmcnt(2)
	ds_read_b128 v[18:21], v129 offset:512
	ds_read_b128 v[14:17], v129 offset:768
	ds_read_b128 v[10:13], v129 offset:16896
	ds_read_b128 v[6:9], v129 offset:17152
	ds_read2_b32 v[62:63], v130 offset0:64 offset1:64
	ds_read2_b32 v[144:145], v130 offset0:96 offset1:96
	v_pk_fma_f32 v[70:71], v[70:71], v[36:37], v[80:81]
	v_pk_fma_f32 v[76:77], v[36:37], v[76:77], v[142:143]
	v_pk_fma_f32 v[64:65], v[64:65], v[34:35], v[80:81]
	v_pk_fma_f32 v[78:79], v[34:35], v[82:83], v[142:143]
	v_pk_fma_f32 v[82:83], v[68:69], v[30:31], v[80:81]
	v_pk_fma_f32 v[84:85], v[74:75], v[30:31], v[142:143]
	v_pk_fma_f32 v[86:87], v[66:67], v[32:33], v[80:81]
	v_pk_fma_f32 v[88:89], v[72:73], v[32:33], v[142:143]
	v_pk_mul_f32 v[30:31], v[28:29], v[70:71]
	v_pk_mul_f32 v[28:29], v[28:29], v[76:77]
	v_pk_fma_f32 v[30:31], v[26:27], v[64:65], v[30:31]
	v_pk_fma_f32 v[26:27], v[26:27], v[78:79], v[28:29]
	v_pk_fma_f32 v[28:29], v[24:25], v[86:87], v[30:31]
	v_pk_fma_f32 v[24:25], v[24:25], v[88:89], v[26:27]
	v_pk_fma_f32 v[28:29], v[22:23], v[82:83], v[28:29]
	v_pk_fma_f32 v[22:23], v[22:23], v[84:85], v[24:25]
	v_add_f32_e32 v4, v28, v29
	v_add_f32_e32 v22, v22, v23
	s_nop 0
	v_add_f32_dpp v4, v4, v4 quad_perm:[1,0,3,2] row_mask:0xf bank_mask:0xf bound_ctrl:1
	v_add_f32_dpp v22, v22, v22 quad_perm:[1,0,3,2] row_mask:0xf bank_mask:0xf bound_ctrl:1
	s_nop 0
	v_add_f32_dpp v4, v4, v4 quad_perm:[2,3,0,1] row_mask:0xf bank_mask:0xf bound_ctrl:1
	v_add_f32_dpp v22, v22, v22 quad_perm:[2,3,0,1] row_mask:0xf bank_mask:0xf bound_ctrl:1
	s_and_saveexec_b64 s[22:23], s[8:9]
	s_cbranch_execz .LBB0_2168
	ds_write_b32 v132, v4 offset:1024
	ds_write_b32 v131, v22 offset:1024
.LBB0_2168:
	s_or_b64 exec, exec, s[22:23]
	s_waitcnt lgkmcnt(2)
	ds_read_b128 v[34:37], v129 offset:1024
	ds_read_b128 v[30:33], v129 offset:1280
	ds_read_b128 v[26:29], v129 offset:17408
	ds_read_b128 v[22:25], v129 offset:17664
	ds_read2_b32 v[66:67], v130 offset0:128 offset1:128
	ds_read2_b32 v[136:137], v130 offset0:160 offset1:160
	v_pk_fma_f32 v[70:71], v[20:21], v[70:71], v[62:63]
	v_pk_fma_f32 v[72:73], v[20:21], v[76:77], v[144:145]
	v_pk_fma_f32 v[64:65], v[18:19], v[64:65], v[62:63]
	v_pk_fma_f32 v[68:69], v[18:19], v[78:79], v[144:145]
	v_pk_fma_f32 v[74:75], v[14:15], v[82:83], v[62:63]
	v_pk_fma_f32 v[80:81], v[14:15], v[84:85], v[144:145]
	v_pk_fma_f32 v[82:83], v[16:17], v[86:87], v[62:63]
	v_pk_fma_f32 v[84:85], v[16:17], v[88:89], v[144:145]
	v_pk_mul_f32 v[14:15], v[12:13], v[70:71]
	v_pk_mul_f32 v[12:13], v[12:13], v[72:73]
	v_pk_fma_f32 v[14:15], v[10:11], v[64:65], v[14:15]
	v_pk_fma_f32 v[10:11], v[10:11], v[68:69], v[12:13]
	v_pk_fma_f32 v[12:13], v[8:9], v[82:83], v[14:15]
	v_pk_fma_f32 v[8:9], v[8:9], v[84:85], v[10:11]
	v_pk_fma_f32 v[12:13], v[6:7], v[74:75], v[12:13]
	v_pk_fma_f32 v[6:7], v[6:7], v[80:81], v[8:9]
	v_add_f32_e32 v4, v12, v13
	v_add_f32_e32 v6, v6, v7
	s_nop 0
	v_add_f32_dpp v4, v4, v4 quad_perm:[1,0,3,2] row_mask:0xf bank_mask:0xf bound_ctrl:1
	v_add_f32_dpp v6, v6, v6 quad_perm:[1,0,3,2] row_mask:0xf bank_mask:0xf bound_ctrl:1
	s_nop 0
	v_add_f32_dpp v4, v4, v4 quad_perm:[2,3,0,1] row_mask:0xf bank_mask:0xf bound_ctrl:1
	v_add_f32_dpp v6, v6, v6 quad_perm:[2,3,0,1] row_mask:0xf bank_mask:0xf bound_ctrl:1
	s_and_saveexec_b64 s[22:23], s[8:9]
	s_cbranch_execz .LBB0_2170
	ds_write_b32 v132, v4 offset:2048
	ds_write_b32 v131, v6 offset:2048
.LBB0_2170:
	s_or_b64 exec, exec, s[22:23]
	s_waitcnt lgkmcnt(2)
	v_pk_fma_f32 v[70:71], v[70:71], v[36:37], v[66:67]
	v_pk_fma_f32 v[76:77], v[36:37], v[72:73], v[136:137]
	v_pk_fma_f32 v[64:65], v[64:65], v[34:35], v[66:67]
	v_pk_fma_f32 v[62:63], v[34:35], v[68:69], v[136:137]
	v_pk_fma_f32 v[68:69], v[74:75], v[30:31], v[66:67]
	v_pk_fma_f32 v[74:75], v[80:81], v[30:31], v[136:137]
	v_pk_fma_f32 v[66:67], v[82:83], v[32:33], v[66:67]
	v_pk_fma_f32 v[72:73], v[84:85], v[32:33], v[136:137]
	v_pk_mul_f32 v[30:31], v[28:29], v[70:71]
	v_pk_mul_f32 v[28:29], v[28:29], v[76:77]
	v_pk_fma_f32 v[30:31], v[26:27], v[64:65], v[30:31]
	v_pk_fma_f32 v[26:27], v[26:27], v[62:63], v[28:29]
	v_pk_fma_f32 v[28:29], v[24:25], v[66:67], v[30:31]
	v_pk_fma_f32 v[24:25], v[24:25], v[72:73], v[26:27]
	v_pk_fma_f32 v[28:29], v[22:23], v[68:69], v[28:29]
	v_pk_fma_f32 v[22:23], v[22:23], v[74:75], v[24:25]
	v_add_f32_e32 v24, v28, v29
	v_add_f32_e32 v23, v22, v23
	ds_read2_b32 v[78:79], v130 offset0:192 offset1:192
	ds_read2_b32 v[140:141], v130 offset0:224 offset1:224
	ds_read_b128 v[18:21], v129 offset:1536
	ds_read_b128 v[14:17], v129 offset:1792
	ds_read_b128 v[10:13], v129 offset:17920
	ds_read_b128 v[6:9], v129 offset:18176
	v_add_f32_dpp v22, v24, v24 quad_perm:[1,0,3,2] row_mask:0xf bank_mask:0xf bound_ctrl:1
	v_add_f32_dpp v23, v23, v23 quad_perm:[1,0,3,2] row_mask:0xf bank_mask:0xf bound_ctrl:1
	s_nop 0
	v_add_f32_dpp v22, v22, v22 quad_perm:[2,3,0,1] row_mask:0xf bank_mask:0xf bound_ctrl:1
	v_add_f32_dpp v23, v23, v23 quad_perm:[2,3,0,1] row_mask:0xf bank_mask:0xf bound_ctrl:1
	s_and_saveexec_b64 s[22:23], s[8:9]
	s_cbranch_execz .LBB0_2163
	ds_write_b32 v132, v22 offset:3072
	ds_write_b32 v131, v23 offset:3072
	s_branch .LBB0_2163
